# E21: pool-mixer trailing-mean loop software-pipelined (next row LDS reads before division chain); on E20
# baseline (speedup 1.0000x reference)
.LBB0_484:
	ds_read_u16 v11, v7
	s_add_i32 s42, s42, -1
	v_add_u32_e32 v7, 0xfffffef0, v7
	s_cmp_lg_u32 s42, 0
	s_waitcnt lgkmcnt(0)
	v_lshlrev_b32_e32 v11, 16, v11
	v_add_f32_e32 v9, v9, v11
	s_cbranch_scc1 .LBB0_484
	v_sub_u32_e32 v7, s51, v6
	v_min_i32_e32 v7, 32, v7
	v_add_u32_e32 v7, v7, v6
	v_add_u32_e32 v8, s97, v8
	s_add_i32 s44, s49, 1
	s_mov_b64 s[42:43], 0
	s_mul_i32 s45, s18, 0xfffffef0
	ds_read_u16 v11, v8
	v_add_u32_e32 v19, s45, v8
	ds_read_u16 v18, v19 offset:272
.LBB0_486:
	v_add_u32_e32 v12, s44, v6
	v_min_i32_e32 v12, s18, v12
	v_mov_b32_e32 v13, s18
	v_cndmask_b32_e64 v12, v12, v13, s[4:5]
	v_cvt_f32_i32_e32 v12, v12
	s_waitcnt lgkmcnt(0)
	v_lshlrev_b32_e32 v21, 16, v11
	v_lshlrev_b32_e32 v20, 16, v18
	v_add_u32_e32 v8, 0x110, v8
	v_add_u32_e32 v19, 0x110, v19
	ds_read_u16 v11, v8
	ds_read_u16 v18, v19 offset:272
	v_add_f32_e32 v9, v9, v21
	v_div_scale_f32 v13, s[46:47], v12, v12, v9
	v_rcp_f32_e32 v14, v13
	v_add_u32_e32 v6, 1, v6
	v_fma_f32 v15, -v13, v14, 1.0
	v_fmac_f32_e32 v14, v15, v14
	v_div_scale_f32 v15, vcc, v9, v12, v9
	v_mul_f32_e32 v16, v15, v14
	v_fma_f32 v17, -v13, v16, v15
	v_fmac_f32_e32 v16, v17, v14
	v_fma_f32 v13, -v13, v16, v15
	v_div_fmas_f32 v13, v13, v14, v16
	v_div_fixup_f32 v12, v13, v12, v9
	v_sub_f32_e32 v13, v12, v21
	v_cvt_pk_bf16_f32 v13, v13, s0
	ds_write_b16 v8, v13 offset:34816
	v_cmp_ge_i32_e32 vcc, v6, v7
	s_or_b64 s[42:43], vcc, s[42:43]
	v_sub_f32_e32 v9, v9, v20
	s_andn2_b64 exec, exec, s[42:43]
	s_cbranch_execnz .LBB0_486
.LBB0_487:
	s_waitcnt lgkmcnt(0)
	s_or_b64 exec, exec, s[6:7]
	v_lshrrev_b32_e32 v6, 1, v10
	v_and_b32_e32 v6, 0x60, v6
	v_cmp_gt_u32_e32 vcc, s51, v6
	s_barrier
	s_and_saveexec_b64 s[6:7], vcc
	s_cbranch_execz .LBB0_521
	s_lshl_b32 s44, s58, 7
	v_and_b32_e32 v4, 0xffffffc0, v4
	v_add_u32_e32 v42, s44, v4
	v_or_b32_e32 v12, v42, v212
	v_ashrrev_i32_e32 v13, 31, v12
	v_lshlrev_b64 v[8:9], 8, v[12:13]
	v_lshl_add_u64 v[60:61], v[162:163], 0, v[8:9]
	global_load_dwordx4 v[8:11], v[60:61], off
	global_load_dwordx4 v[38:41], v[60:61], off offset:32
	v_or_b32_e32 v12, 32, v12
	v_ashrrev_i32_e32 v13, 31, v12
	v_lshlrev_b64 v[12:13], 8, v[12:13]
	v_lshl_add_u64 v[62:63], v[162:163], 0, v[12:13]
	global_load_dwordx4 v[12:15], v[62:63], off
	v_or_b32_e32 v43, v6, v212
	v_mad_u32_u24 v64, v43, s3, v192
	ds_read_b128 v[16:19], v64 offset:39168
	ds_read_b128 v[44:47], v64 offset:39200
	global_load_dwordx4 v[48:51], v[62:63], off offset:32
	global_load_dwordx4 v[52:55], v[60:61], off offset:64
	v_cmp_gt_u32_e32 vcc, s51, v43
	s_waitcnt vmcnt(4) lgkmcnt(1)
	v_mfma_f32_32x32x16_bf16 v[22:37], v[8:11], v[16:19], 0
	s_waitcnt vmcnt(2)
	v_mfma_f32_32x32x16_bf16 v[6:21], v[12:15], v[16:19], 0
	s_waitcnt lgkmcnt(0)
	v_mfma_f32_32x32x16_bf16 v[22:37], v[38:41], v[44:47], v[22:37]
	global_load_dwordx4 v[38:41], v[62:63], off offset:64
	s_waitcnt vmcnt(2)
	v_mfma_f32_32x32x16_bf16 v[6:21], v[48:51], v[44:47], v[6:21]
	global_load_dwordx4 v[44:47], v[60:61], off offset:96
	ds_read_b128 v[48:51], v64 offset:39232
	ds_read_b128 v[56:59], v64 offset:39264
	s_waitcnt vmcnt(2) lgkmcnt(1)
	v_mfma_f32_32x32x16_bf16 v[22:37], v[52:55], v[48:51], v[22:37]
	global_load_dwordx4 v[52:55], v[62:63], off offset:96
	s_waitcnt vmcnt(2)
	v_mfma_f32_32x32x16_bf16 v[6:21], v[38:41], v[48:51], v[6:21]
	global_load_dwordx4 v[38:41], v[60:61], off offset:128
	global_load_dwordx4 v[48:51], v[60:61], off offset:160
	s_waitcnt vmcnt(3) lgkmcnt(0)
	v_mfma_f32_32x32x16_bf16 v[22:37], v[44:47], v[56:59], v[22:37]
	global_load_dwordx4 v[44:47], v[62:63], off offset:128
	s_waitcnt vmcnt(3)
	v_mfma_f32_32x32x16_bf16 v[6:21], v[52:55], v[56:59], v[6:21]
	ds_read_b128 v[52:55], v64 offset:39296
	ds_read_b128 v[56:59], v64 offset:39328
	s_waitcnt vmcnt(2) lgkmcnt(1)
	v_mfma_f32_32x32x16_bf16 v[22:37], v[38:41], v[52:55], v[22:37]
	global_load_dwordx4 v[38:41], v[62:63], off offset:160
	s_waitcnt vmcnt(1)
	v_mfma_f32_32x32x16_bf16 v[6:21], v[44:47], v[52:55], v[6:21]
	global_load_dwordx4 v[44:47], v[60:61], off offset:192
	s_waitcnt lgkmcnt(0)
	v_mfma_f32_32x32x16_bf16 v[22:37], v[48:51], v[56:59], v[22:37]
	global_load_dwordx4 v[48:51], v[62:63], off offset:192
	s_waitcnt vmcnt(2)
	v_mfma_f32_32x32x16_bf16 v[6:21], v[38:41], v[56:59], v[6:21]
	global_load_dwordx4 v[38:41], v[60:61], off offset:224
	ds_read_b128 v[52:55], v64 offset:39360
	ds_read_b128 v[56:59], v64 offset:39392
	s_waitcnt vmcnt(2) lgkmcnt(1)
	v_mfma_f32_32x32x16_bf16 v[22:37], v[44:47], v[52:55], v[22:37]
	global_load_dwordx4 v[44:47], v[62:63], off offset:224
	s_waitcnt vmcnt(2)
	v_mfma_f32_32x32x16_bf16 v[6:21], v[48:51], v[52:55], v[6:21]
	s_waitcnt vmcnt(1) lgkmcnt(0)
	v_mfma_f32_32x32x16_bf16 v[22:37], v[38:41], v[56:59], v[22:37]
	s_waitcnt vmcnt(0)
	v_mfma_f32_32x32x16_bf16 v[6:21], v[44:47], v[56:59], v[6:21]
	s_and_b64 exec, exec, vcc
	s_cbranch_execz .LBB0_521
	s_add_i32 s45, s49, s50
	s_lshl_b32 s18, s44, 1
	s_lshl_b32 s4, s44, 2
	v_or_b32_e32 v38, v4, v216
	s_add_u32 s4, s8, s4
	s_addc_u32 s5, s9, 0
	v_ashrrev_i32_e32 v39, 31, v38
	v_lshl_add_u64 v[40:41], v[38:39], 2, s[4:5]
	global_load_dwordx4 v[44:47], v[40:41], off
	v_cndmask_b32_e64 v48, 0, 1, s[40:41]
	v_add_u32_e32 v4, s45, v43
	v_cmp_ne_u32_e64 s[4:5], 1, v48
	v_lshlrev_b64 v[48:49], 11, v[4:5]
	v_lshl_add_u64 v[48:49], s[24:25], 0, v[48:49]
	v_lshl_add_u64 v[48:49], v[48:49], 0, s[18:19]
	s_mov_b64 s[42:43], -1
	s_andn2_b64 vcc, exec, s[40:41]
	s_waitcnt vmcnt(0)
	v_pk_mul_f32 v[22:23], v[22:23], v[44:45]
	v_pk_mul_f32 v[24:25], v[24:25], v[46:47]
	v_cvt_pk_bf16_f32 v44, v22, v23
	v_cvt_pk_bf16_f32 v45, v24, v25
	v_lshl_add_u64 v[22:23], v[38:39], 1, v[48:49]
	s_cbranch_vccnz .LBB0_491
	s_mov_b64 s[42:43], 0
	global_store_dwordx2 v[22:23], v[44:45], off
